# hardware transpose read in ma_ret j-loop: K and V staged row-major with 6 ds_write_b128 (swizzled image) instead of 48 16-bit transposed writes; operands read with ds_read_b64_tr_b16, 5-deep pipelined
# speedup vs baseline: 1.0104x; 1.0028x over previous
; __device__ __forceinline__ int otid() { int t = threadIdx.x; asm volatile("" : "+v"(t)); return t; }
; __device__ __forceinline__ void ma_ret_item(const Params& p, ldsp lds, int item) {
;     const int tid = otid(), lane = tid & 63, wave = __builtin_amdgcn_readfirstlane(tid >> 6), l15 = lane & 15, q4 = lane >> 4;
;     const int es = item & 3, sc = (item >> 2) & 7, bh = item >> 5, b = bh >> 2, h = bh & 3;
;     ldsp KTt = lds; ldsp VTt = lds + 36864;
;     const bf16_t* Pb = (const bf16_t*)(p.ws + WS_P);
;     f32x4 acc[16];
; #pragma unroll
;     for (int i = 0; i < 16; ++i) acc[i] = (f32x4){0.f, 0.f, 0.f, 0.f};
;     u32x4 kr[4], vr[2];
;     { const size_t rowq = (size_t)b * 2048 + (sc * 4) * 64;
;       ld_T<256>(kr, Pb + rowq * NO + O_K + h * 256, NO, wave, lane); ld_T<128>(vr, Pb + rowq * NO + O_V + h * 512 + es * 128, NO, wave, lane); }
.LBB0_677:
	s_lshl_b32 s0, s12, 6
	v_readlane_b32 s1, v253, 36
	s_add_i32 s0, s1, s0
	s_ashr_i32 s10, s0, 5
	s_ashr_i32 s11, s10, 31
	s_lshl_b64 s[8:9], s[10:11], 11
	v_readlane_b32 s11, v253, 37
	v_mov_b32_e32 v2, v161
	s_or_b32 s8, s8, s11
	s_ashr_i32 s0, s0, 3
	v_readfirstlane_b32 s1, v2
	s_mulk_i32 s9, 0x3000
	s_mul_hi_u32 s11, s8, 0x3000
	s_ashr_i32 s1, s1, 6
	s_and_b32 s13, s0, 3
	s_add_i32 s11, s11, s9
	s_mulk_i32 s8, 0x3000
	s_add_u32 s14, s26, s8
	s_addc_u32 s11, s27, s11
	s_lshl_b32 s15, s13, 9
	s_add_u32 s8, s14, s15
	s_addc_u32 s9, s11, 0
	s_lshl_b32 s16, s1, 5
	v_and_b32_e32 v0, 31, v2
	v_and_or_b32 v29, s16, 32, v0
	v_mul_u32_u24_e32 v0, 0x1800, v29
	v_lshlrev_b32_e32 v16, 1, v0
	v_lshl_add_u64 v[0:1], s[8:9], 0, v[16:17]
	s_and_b32 s8, s1, 0x1ffffffe
	v_bfe_u32 v30, v2, 5, 1
	v_and_b32_e32 v95, 15, v2
	v_bfe_u32 v28, v2, 4, 2
	v_or_b32_e32 v2, s8, v30
	s_lshl_b32 s13, s13, 10
	v_lshlrev_b32_e32 v2, 3, v2
	s_add_u32 s8, s14, s13
	v_ashrrev_i32_e32 v3, 31, v2
	s_addc_u32 s9, s11, 0
	v_readlane_b32 s11, v255, 11
	v_lshlrev_b64 v[26:27], 1, v[2:3]
	s_add_u32 s8, s8, s11
	v_lshl_add_u64 v[0:1], v[0:1], 0, v[26:27]
	s_addc_u32 s9, s9, 0
	global_load_dwordx4 v[22:25], v[0:1], off offset:2048
	global_load_dwordx4 v[18:21], v[0:1], off offset:2176
	global_load_dwordx4 v[12:15], v[0:1], off offset:2304
	global_load_dwordx4 v[4:7], v[0:1], off offset:2432
	v_lshl_add_u64 v[0:1], s[8:9], 0, v[16:17]
	v_lshl_add_u64 v[0:1], v[0:1], 0, v[26:27]
	s_mov_b64 s[8:9], 0x1000
	v_lshl_add_u64 v[2:3], v[0:1], 0, s[8:9]
	v_add_co_u32_e32 v0, vcc, s57, v0
	s_and_b32 s8, s1, 0x3fffffe
	s_nop 0
	v_addc_co_u32_e32 v1, vcc, 0, v1, vcc
	global_load_dwordx4 v[8:11], v[0:1], off
	s_nop 0
	global_load_dwordx4 v[0:3], v[2:3], off offset:128
	v_or_b32_e32 v30, s8, v30
	s_movk_i32 s8, 0x240
	v_mul_lo_u32 v30, v30, s8
	v_or_b32_e32 v29, v29, v30
	s_lshl_b32 s8, s1, 4
	v_lshl_add_u32 v100, v29, 1, 0
	v_or_b32_e32 v29, s8, v95
	v_lshlrev_b32_e32 v94, 3, v28
	v_mul_lo_u32 v29, v29, s53
	v_or_b32_e32 v28, 32, v94
	v_mul_u32_u24_e32 v30, 0x48, v95
	v_add_lshl_u32 v31, v28, v30, 1
	v_add_lshl_u32 v32, v29, v94, 1
	v_add_lshl_u32 v33, v94, v30, 1
	v_mov_b32_e32 v29, 0x480
	v_mov_b32_e32 v30, 0x900
	v_mov_b32_e32 v36, 0xd80
	v_mov_b32_e32 v38, 0x1200
	v_mov_b32_e32 v40, 0x1680
	v_mov_b32_e32 v42, 0x1b00
	v_mov_b32_e32 v44, 0x1f80
	v_mov_b32_e32 v46, 0x2400
	v_mov_b32_e32 v48, 0x2880
	v_mov_b32_e32 v50, 0x2d00
	v_mov_b32_e32 v52, 0x3180
	v_mov_b32_e32 v54, 0x3600
	v_mov_b32_e32 v56, 0x3a80
	v_mov_b32_e32 v58, 0x3f00
	v_mov_b32_e32 v60, 0x4380
	s_mul_i32 s1, s10, 0x1800000
	v_mad_u32_u24 v29, v95, s53, v29
	v_mad_u32_u24 v30, v95, s53, v30
	v_mad_u32_u24 v36, v95, s53, v36
	v_mad_u32_u24 v38, v95, s53, v38
	v_mad_u32_u24 v40, v95, s53, v40
	v_mad_u32_u24 v42, v95, s53, v42
	v_mad_u32_u24 v44, v95, s53, v44
	v_mad_u32_u24 v46, v95, s53, v46
	v_mad_u32_u24 v48, v95, s53, v48
	v_mad_u32_u24 v50, v95, s53, v50
	v_mad_u32_u24 v52, v95, s53, v52
	v_mad_u32_u24 v54, v95, s53, v54
	v_mad_u32_u24 v56, v95, s53, v56
	v_mad_u32_u24 v58, v95, s53, v58
	v_mad_u32_u24 v60, v95, s53, v60
	s_mul_hi_i32 s11, s10, 0x1800000
	s_or_b32 s10, s1, s13
	v_add_lshl_u32 v34, v94, v29, 1
	v_add_lshl_u32 v37, v94, v36, 1
	v_add_lshl_u32 v39, v94, v38, 1
	v_add_lshl_u32 v41, v94, v40, 1
	v_add_lshl_u32 v43, v94, v42, 1
	v_add_lshl_u32 v45, v94, v44, 1
	v_add_lshl_u32 v47, v94, v46, 1
	v_add_lshl_u32 v49, v94, v48, 1
	v_add_lshl_u32 v51, v94, v50, 1
	v_add_lshl_u32 v53, v94, v52, 1
	v_add_lshl_u32 v55, v94, v54, 1
	v_add_lshl_u32 v57, v94, v56, 1
	v_add_lshl_u32 v59, v94, v58, 1
	v_add_lshl_u32 v61, v94, v60, 1
	v_add_lshl_u32 v62, v28, v29, 1
	v_add_lshl_u32 v63, v28, v30, 1
	v_add_lshl_u32 v36, v28, v36, 1
	v_add_lshl_u32 v38, v28, v38, 1
	v_add_lshl_u32 v40, v28, v40, 1
	v_add_lshl_u32 v42, v28, v42, 1
	v_add_lshl_u32 v44, v28, v44, 1
	v_add_lshl_u32 v46, v28, v46, 1
	v_add_lshl_u32 v48, v28, v48, 1
	v_add_lshl_u32 v50, v28, v50, 1
	v_add_lshl_u32 v52, v28, v52, 1
	v_add_lshl_u32 v54, v28, v54, 1
	v_add_lshl_u32 v56, v28, v56, 1
	v_add_lshl_u32 v58, v28, v58, 1
	v_add_lshl_u32 v60, v28, v60, 1
	v_lshl_add_u64 v[28:29], s[10:11], 0, v[26:27]
	s_or_b32 s10, s1, s15
	v_readlane_b32 s16, v254, 51
	v_lshl_add_u64 v[26:27], s[10:11], 0, v[26:27]
	v_readlane_b32 s10, v254, 53
	v_add_lshl_u32 v35, v94, v30, 1
	v_lshl_add_u64 v[28:29], v[28:29], 0, v[16:17]
	v_readlane_b32 s17, v254, 52
	v_lshl_add_u64 v[26:27], v[26:27], 0, v[16:17]
	v_readlane_b32 s11, v254, 54
	v_mov_b32_e32 v30, 0
	v_lshl_add_u64 v[96:97], s[16:17], 0, v[28:29]
	v_lshl_add_u64 v[98:99], s[10:11], 0, v[26:27]
	s_mov_b64 s[10:11], 0
	v_add_u32_e32 v130, 0, v32
	v_add_u32_e32 v132, 0, v33
	v_add_u32_e32 v131, 0, v34
	v_add_u32_e32 v129, 0, v35
	v_add_u32_e32 v128, 0, v37
	v_add_u32_e32 v127, 0, v39
	v_add_u32_e32 v126, 0, v41
	v_add_u32_e32 v125, 0, v43
	v_add_u32_e32 v124, 0, v45
	v_add_u32_e32 v123, 0, v47
	v_add_u32_e32 v122, 0, v49
	v_add_u32_e32 v121, 0, v51
	v_add_u32_e32 v120, 0, v53
	v_add_u32_e32 v119, 0, v55
	v_add_u32_e32 v118, 0, v57
	v_add_u32_e32 v117, 0, v59
	v_add_u32_e32 v116, 0, v61
	v_add_u32_e32 v115, 0, v31
	v_add_u32_e32 v114, 0, v62
	v_add_u32_e32 v113, 0, v63
	v_add_u32_e32 v112, 0, v36
	v_add_u32_e32 v111, 0, v38
	v_add_u32_e32 v110, 0, v40
	v_add_u32_e32 v109, 0, v42
	v_add_u32_e32 v108, 0, v44
	v_add_u32_e32 v107, 0, v46
	v_add_u32_e32 v106, 0, v48
	v_add_u32_e32 v105, 0, v50
	v_add_u32_e32 v104, 0, v52
	v_add_u32_e32 v103, 0, v54
	v_add_u32_e32 v102, 0, v56
	v_add_u32_e32 v101, 0, v58
	v_add_u32_e32 v16, 0, v60
	v_mov_b32_e32 v31, v30
	v_mov_b32_e32 v32, v30
	v_mov_b32_e32 v33, v30
	v_mov_b32_e32 v86, v30
; __device__ __forceinline__ f32x4 mma16(bf16x8 a, bf16x8 b, f32x4 c) { return __builtin_amdgcn_mfma_f32_16x16x32_bf16(a, b, c, 0, 0, 0); }
; __device__ __forceinline__ void ma_ret_item(const Params& p, ldsp lds, int item) {
;     ...
;     f32x4 acc[16];
; #pragma unroll
;     for (int i = 0; i < 16; ++i) acc[i] = (f32x4){0.f, 0.f, 0.f, 0.f};
;     u32x4 kr[4], vr[2];
;     { const size_t rowq = (size_t)b * 2048 + (sc * 4) * 64;
;       ld_T<256>(kr, Pb + rowq * NO + O_K + h * 256, NO, wave, lane); ld_T<128>(vr, Pb + rowq * NO + O_V + h * 512 + es * 128, NO, wave, lane); }
;     for (int j = 0; j < 4; ++j) { const size_t rowj = (size_t)b * 2048 + (sc * 4 + j) * 64;
;         st_T<256>(KTt, 72, kr, wave, lane); st_T<128>(VTt, 72, vr, wave, lane);
;         __syncthreads();
;         if (j < 3) { const size_t rown = rowj + 64; ld_T<256>(kr, Pb + rown * NO + O_K + h * 256, NO, wave, lane); ld_T<128>(vr, Pb + rown * NO + O_V + h * 512 + es * 128, NO, wave, lane); }
; #pragma unroll
;         for (int ks = 0; ks < 2; ++ks) { const bf16x8 bf = ldfrag(VTt, (16 * wave + l15) * 72 + 32 * ks + 8 * q4);
; #pragma unroll
;             for (int i = 0; i < 16; ++i) acc[i] = mma16(ldfrag(KTt, (16 * i + l15) * 72 + 32 * ks + 8 * q4), bf, acc[i]); }
	v_mov_b32_e32 v87, v30
	v_mov_b32_e32 v88, v30
	v_mov_b32_e32 v89, v30
	v_mov_b32_e32 v82, v30
	v_mov_b32_e32 v83, v30
	v_mov_b32_e32 v84, v30
	v_mov_b32_e32 v85, v30
	v_mov_b32_e32 v78, v30
	v_mov_b32_e32 v79, v30
	v_mov_b32_e32 v80, v30
	v_mov_b32_e32 v81, v30
	v_mov_b32_e32 v74, v30
	v_mov_b32_e32 v75, v30
	v_mov_b32_e32 v76, v30
	v_mov_b32_e32 v77, v30
	v_mov_b32_e32 v70, v30
	v_mov_b32_e32 v71, v30
	v_mov_b32_e32 v72, v30
	v_mov_b32_e32 v73, v30
	v_mov_b32_e32 v66, v30
	v_mov_b32_e32 v67, v30
	v_mov_b32_e32 v68, v30
	v_mov_b32_e32 v69, v30
	v_mov_b32_e32 v62, v30
	v_mov_b32_e32 v63, v30
	v_mov_b32_e32 v64, v30
	v_mov_b32_e32 v65, v30
	v_mov_b32_e32 v58, v30
	v_mov_b32_e32 v59, v30
	v_mov_b32_e32 v60, v30
	v_mov_b32_e32 v61, v30
	v_mov_b32_e32 v54, v30
	v_mov_b32_e32 v55, v30
	v_mov_b32_e32 v56, v30
	v_mov_b32_e32 v57, v30
	v_mov_b32_e32 v50, v30
	v_mov_b32_e32 v51, v30
	v_mov_b32_e32 v52, v30
	v_mov_b32_e32 v53, v30
	v_mov_b32_e32 v46, v30
	v_mov_b32_e32 v47, v30
	v_mov_b32_e32 v48, v30
	v_mov_b32_e32 v49, v30
	v_mov_b32_e32 v42, v30
	v_mov_b32_e32 v43, v30
	v_mov_b32_e32 v44, v30
	v_mov_b32_e32 v45, v30
	v_mov_b32_e32 v38, v30
	v_mov_b32_e32 v39, v30
	v_mov_b32_e32 v40, v30
	v_mov_b32_e32 v41, v30
	v_mov_b32_e32 v34, v30
	v_mov_b32_e32 v35, v30
	v_mov_b32_e32 v36, v30
	v_mov_b32_e32 v37, v30
	v_mov_b32_e32 v26, v30
	v_mov_b32_e32 v27, v30
	v_mov_b32_e32 v28, v30
	v_mov_b32_e32 v29, v30
	v_and_b32_e32 v176, 31, v161
	v_bfe_u32 v177, v161, 6, 1
	v_lshl_or_b32 v176, v177, 5, v176
	v_lshrrev_b32_e32 v178, 7, v161
	v_bfe_u32 v179, v161, 5, 1
	v_lshl_or_b32 v178, v178, 1, v179
	v_and_b32_e32 v179, 3, v176
	v_bfe_u32 v180, v176, 2, 2
	v_lshl_or_b32 v179, v179, 2, v180
	v_and_b32_e32 v180, 7, v179
	v_xor_b32_e32 v180, v178, v180
	v_lshrrev_b32_e32 v179, 3, v179
	v_lshlrev_b32_e32 v176, 8, v176
	v_lshl_add_u32 v176, v180, 4, v176
	v_lshl_add_u32 v172, v179, 7, v176
	v_xor_b32_e32 v173, 0x80, v172
	v_add_u32_e32 v174, 0x9000, v172
	v_add_u32_e32 v175, 0x9000, v173
	v_bfe_u32 v176, v161, 4, 2
	v_bfe_u32 v177, v161, 2, 2
	v_and_b32_e32 v178, 3, v161
	v_lshl_or_b32 v179, v176, 3, v177
	v_lshlrev_b32_e32 v180, 1, v176
	v_and_b32_e32 v180, 3, v180
	v_lshl_or_b32 v180, v177, 2, v180
	v_lshrrev_b32_e32 v177, 1, v178
	v_xor_b32_e32 v176, v177, v180
	v_and_b32_e32 v178, 1, v178
	v_lshlrev_b32_e32 v179, 8, v179
	v_lshl_add_u32 v179, v176, 4, v179
	v_lshl_add_u32 v140, v178, 3, v179
	v_xor_b32_e32 v148, 16, v140
	v_add_u32_e32 v148, 0x400, v148
	v_xor_b32_e32 v141, 32, v140
	v_xor_b32_e32 v149, 32, v148
	v_xor_b32_e32 v142, 64, v140
	v_xor_b32_e32 v150, 64, v148
	v_xor_b32_e32 v143, 0x60, v140
	v_xor_b32_e32 v151, 0x60, v148
	v_xor_b32_e32 v144, 0x80, v140
	v_xor_b32_e32 v152, 0x80, v148
	v_xor_b32_e32 v145, 0xa0, v140
	v_xor_b32_e32 v153, 0xa0, v148
	v_xor_b32_e32 v146, 0xc0, v140
	v_xor_b32_e32 v154, 0xc0, v148
	v_xor_b32_e32 v147, 0xe0, v140
	v_xor_b32_e32 v155, 0xe0, v148
	v_lshrrev_b32_e32 v176, 6, v161
	v_lshlrev_b32_e32 v176, 5, v176
	v_xor_b32_e32 v156, v176, v140
	v_xor_b32_e32 v157, v176, v148
	v_add_u32_e32 v156, 0x9000, v156
	v_add_u32_e32 v157, 0x9000, v157
.LBB0_678:
	s_waitcnt vmcnt(5)
	ds_write_b128 v172, v[22:25]
	s_waitcnt vmcnt(4)
	ds_write_b128 v173, v[18:21]
	s_waitcnt vmcnt(3)
	ds_write_b128 v172, v[12:15] offset:16384
	s_waitcnt vmcnt(2)
	ds_write_b128 v173, v[4:7] offset:16384
	s_waitcnt vmcnt(1)
	ds_write_b128 v174, v[8:11]
	s_waitcnt vmcnt(0)
	ds_write_b128 v175, v[0:3]
	v_lshl_add_u64 v[0:1], v[98:99], 0, s[10:11]
	s_waitcnt lgkmcnt(0)
	s_barrier
	global_load_dwordx4 v[22:25], v[0:1], off offset:-256
	global_load_dwordx4 v[18:21], v[0:1], off offset:-128
	global_load_dwordx4 v[12:15], v[0:1], off
	global_load_dwordx4 v[4:7], v[0:1], off offset:128
	v_lshl_add_u64 v[0:1], v[96:97], 0, s[10:11]
	v_add_co_u32_e32 v0, vcc, s54, v0
	s_add_u32 s10, s10, 0xc0000
	s_nop 0
	v_addc_co_u32_e32 v1, vcc, 0, v1, vcc
	global_load_dwordx4 v[8:11], v[0:1], off
	s_nop 0
	global_load_dwordx4 v[0:3], v[0:1], off offset:128
	ds_read_b64_tr_b16 v[90:91], v156
	ds_read_b64_tr_b16 v[92:93], v157
	ds_read_b64_tr_b16 v[242:243], v156 offset:8192
	ds_read_b64_tr_b16 v[244:245], v157 offset:8192
	ds_read_b64_tr_b16 v[210:211], v140
	ds_read_b64_tr_b16 v[212:213], v148
	ds_read_b64_tr_b16 v[214:215], v141
	ds_read_b64_tr_b16 v[216:217], v149
	ds_read_b64_tr_b16 v[218:219], v142
	ds_read_b64_tr_b16 v[220:221], v150
	ds_read_b64_tr_b16 v[222:223], v143
	ds_read_b64_tr_b16 v[224:225], v151
	ds_read_b64_tr_b16 v[226:227], v144
	ds_read_b64_tr_b16 v[228:229], v152
	s_addc_u32 s11, s11, 0
	s_cmp_lg_u32 s10, 0x240000
	s_waitcnt lgkmcnt(8)
	v_mfma_f32_16x16x32_bf16 v[26:29], v[210:213], v[90:93], v[26:29]
	ds_read_b64_tr_b16 v[210:211], v145
	ds_read_b64_tr_b16 v[212:213], v153
	s_waitcnt lgkmcnt(8)
	v_mfma_f32_16x16x32_bf16 v[34:37], v[214:217], v[90:93], v[34:37]
	ds_read_b64_tr_b16 v[214:215], v146
	ds_read_b64_tr_b16 v[216:217], v154
	s_waitcnt lgkmcnt(8)
	v_mfma_f32_16x16x32_bf16 v[38:41], v[218:221], v[90:93], v[38:41]
	ds_read_b64_tr_b16 v[218:219], v147
	ds_read_b64_tr_b16 v[220:221], v155
	s_waitcnt lgkmcnt(8)
	v_mfma_f32_16x16x32_bf16 v[42:45], v[222:225], v[90:93], v[42:45]
	ds_read_b64_tr_b16 v[222:223], v140 offset:16384
	ds_read_b64_tr_b16 v[224:225], v148 offset:16384
	s_waitcnt lgkmcnt(8)
	v_mfma_f32_16x16x32_bf16 v[46:49], v[226:229], v[90:93], v[46:49]
	ds_read_b64_tr_b16 v[226:227], v141 offset:16384
	ds_read_b64_tr_b16 v[228:229], v149 offset:16384
	s_waitcnt lgkmcnt(8)
	v_mfma_f32_16x16x32_bf16 v[50:53], v[210:213], v[90:93], v[50:53]
	ds_read_b64_tr_b16 v[210:211], v142 offset:16384
	ds_read_b64_tr_b16 v[212:213], v150 offset:16384
	s_waitcnt lgkmcnt(8)
; __device__ __forceinline__ f32x4 mma16(bf16x8 a, bf16x8 b, f32x4 c) { return __builtin_amdgcn_mfma_f32_16x16x32_bf16(a, b, c, 0, 0, 0); }
; __device__ __forceinline__ void ma_ret_item(const Params& p, ldsp lds, int item) {
;     ...
;     for (int j = 0; j < 4; ++j) { const size_t rowj = (size_t)b * 2048 + (sc * 4 + j) * 64;
;         st_T<256>(KTt, 72, kr, wave, lane); st_T<128>(VTt, 72, vr, wave, lane);
;         __syncthreads();
;         if (j < 3) { const size_t rown = rowj + 64; ld_T<256>(kr, Pb + rown * NO + O_K + h * 256, NO, wave, lane); ld_T<128>(vr, Pb + rown * NO + O_V + h * 512 + es * 128, NO, wave, lane); }
; #pragma unroll
;         for (int ks = 0; ks < 2; ++ks) { const bf16x8 bf = ldfrag(VTt, (16 * wave + l15) * 72 + 32 * ks + 8 * q4);
; #pragma unroll
;             for (int i = 0; i < 16; ++i) acc[i] = mma16(ldfrag(KTt, (16 * i + l15) * 72 + 32 * ks + 8 * q4), bf, acc[i]); }
;         __syncthreads(); }
	v_mfma_f32_16x16x32_bf16 v[54:57], v[214:217], v[90:93], v[54:57]
	ds_read_b64_tr_b16 v[214:215], v143 offset:16384
	ds_read_b64_tr_b16 v[216:217], v151 offset:16384
	s_waitcnt lgkmcnt(8)
	v_mfma_f32_16x16x32_bf16 v[58:61], v[218:221], v[90:93], v[58:61]
	ds_read_b64_tr_b16 v[218:219], v144 offset:16384
	ds_read_b64_tr_b16 v[220:221], v152 offset:16384
	s_waitcnt lgkmcnt(8)
	v_mfma_f32_16x16x32_bf16 v[62:65], v[222:225], v[90:93], v[62:65]
	ds_read_b64_tr_b16 v[222:223], v145 offset:16384
	ds_read_b64_tr_b16 v[224:225], v153 offset:16384
	s_waitcnt lgkmcnt(8)
	v_mfma_f32_16x16x32_bf16 v[66:69], v[226:229], v[90:93], v[66:69]
	ds_read_b64_tr_b16 v[226:227], v146 offset:16384
	ds_read_b64_tr_b16 v[228:229], v154 offset:16384
	s_waitcnt lgkmcnt(8)
	v_mfma_f32_16x16x32_bf16 v[70:73], v[210:213], v[90:93], v[70:73]
	ds_read_b64_tr_b16 v[210:211], v147 offset:16384
	ds_read_b64_tr_b16 v[212:213], v155 offset:16384
	s_waitcnt lgkmcnt(8)
	v_mfma_f32_16x16x32_bf16 v[74:77], v[214:217], v[90:93], v[74:77]
	ds_read_b64_tr_b16 v[214:215], v140 offset:8192
	ds_read_b64_tr_b16 v[216:217], v148 offset:8192
	s_waitcnt lgkmcnt(8)
	v_mfma_f32_16x16x32_bf16 v[78:81], v[218:221], v[90:93], v[78:81]
	ds_read_b64_tr_b16 v[218:219], v141 offset:8192
	ds_read_b64_tr_b16 v[220:221], v149 offset:8192
	s_waitcnt lgkmcnt(8)
	v_mfma_f32_16x16x32_bf16 v[82:85], v[222:225], v[90:93], v[82:85]
	ds_read_b64_tr_b16 v[222:223], v142 offset:8192
	ds_read_b64_tr_b16 v[224:225], v150 offset:8192
	s_waitcnt lgkmcnt(8)
	v_mfma_f32_16x16x32_bf16 v[86:89], v[226:229], v[90:93], v[86:89]
	ds_read_b64_tr_b16 v[226:227], v143 offset:8192
	ds_read_b64_tr_b16 v[228:229], v151 offset:8192
	s_waitcnt lgkmcnt(8)
	v_mfma_f32_16x16x32_bf16 v[30:33], v[210:213], v[90:93], v[30:33]
	ds_read_b64_tr_b16 v[210:211], v144 offset:8192
	ds_read_b64_tr_b16 v[212:213], v152 offset:8192
	s_waitcnt lgkmcnt(8)
	v_mfma_f32_16x16x32_bf16 v[26:29], v[214:217], v[242:245], v[26:29]
	ds_read_b64_tr_b16 v[214:215], v145 offset:8192
	ds_read_b64_tr_b16 v[216:217], v153 offset:8192
	s_waitcnt lgkmcnt(8)
	v_mfma_f32_16x16x32_bf16 v[34:37], v[218:221], v[242:245], v[34:37]
	ds_read_b64_tr_b16 v[218:219], v146 offset:8192
	ds_read_b64_tr_b16 v[220:221], v154 offset:8192
	s_waitcnt lgkmcnt(8)
	v_mfma_f32_16x16x32_bf16 v[38:41], v[222:225], v[242:245], v[38:41]
	ds_read_b64_tr_b16 v[222:223], v147 offset:8192
	ds_read_b64_tr_b16 v[224:225], v155 offset:8192
	s_waitcnt lgkmcnt(8)
	v_mfma_f32_16x16x32_bf16 v[42:45], v[226:229], v[242:245], v[42:45]
	ds_read_b64_tr_b16 v[226:227], v140 offset:24576
	ds_read_b64_tr_b16 v[228:229], v148 offset:24576
	s_waitcnt lgkmcnt(8)
	v_mfma_f32_16x16x32_bf16 v[46:49], v[210:213], v[242:245], v[46:49]
	ds_read_b64_tr_b16 v[210:211], v141 offset:24576
	ds_read_b64_tr_b16 v[212:213], v149 offset:24576
	s_waitcnt lgkmcnt(8)
	v_mfma_f32_16x16x32_bf16 v[50:53], v[214:217], v[242:245], v[50:53]
	ds_read_b64_tr_b16 v[214:215], v142 offset:24576
	ds_read_b64_tr_b16 v[216:217], v150 offset:24576
	s_waitcnt lgkmcnt(8)
	v_mfma_f32_16x16x32_bf16 v[54:57], v[218:221], v[242:245], v[54:57]
	ds_read_b64_tr_b16 v[218:219], v143 offset:24576
	ds_read_b64_tr_b16 v[220:221], v151 offset:24576
	s_waitcnt lgkmcnt(8)
	v_mfma_f32_16x16x32_bf16 v[58:61], v[222:225], v[242:245], v[58:61]
	ds_read_b64_tr_b16 v[222:223], v144 offset:24576
	ds_read_b64_tr_b16 v[224:225], v152 offset:24576
	s_waitcnt lgkmcnt(8)
	v_mfma_f32_16x16x32_bf16 v[62:65], v[226:229], v[242:245], v[62:65]
	ds_read_b64_tr_b16 v[226:227], v145 offset:24576
	ds_read_b64_tr_b16 v[228:229], v153 offset:24576
	s_waitcnt lgkmcnt(8)
	v_mfma_f32_16x16x32_bf16 v[66:69], v[210:213], v[242:245], v[66:69]
	ds_read_b64_tr_b16 v[210:211], v146 offset:24576
	ds_read_b64_tr_b16 v[212:213], v154 offset:24576
	s_waitcnt lgkmcnt(8)
	v_mfma_f32_16x16x32_bf16 v[70:73], v[214:217], v[242:245], v[70:73]
	ds_read_b64_tr_b16 v[214:215], v147 offset:24576
	ds_read_b64_tr_b16 v[216:217], v155 offset:24576
	s_waitcnt lgkmcnt(8)
	v_mfma_f32_16x16x32_bf16 v[74:77], v[218:221], v[242:245], v[74:77]
	s_waitcnt lgkmcnt(6)
	v_mfma_f32_16x16x32_bf16 v[78:81], v[222:225], v[242:245], v[78:81]
	s_waitcnt lgkmcnt(4)
	v_mfma_f32_16x16x32_bf16 v[82:85], v[226:229], v[242:245], v[82:85]
	s_waitcnt lgkmcnt(2)
	v_mfma_f32_16x16x32_bf16 v[86:89], v[210:213], v[242:245], v[86:89]
	s_waitcnt lgkmcnt(0)
	s_barrier
	v_mfma_f32_16x16x32_bf16 v[30:33], v[214:217], v[242:245], v[30:33]
	s_cbranch_scc1 .LBB0_678
	s_waitcnt vmcnt(5)
	ds_write_b16 v100, v22
	ds_write_b16_d16_hi v100, v22 offset:144
	ds_write_b16 v100, v23 offset:288
	ds_write_b16_d16_hi v100, v23 offset:432
	ds_write_b16 v100, v24 offset:576
	ds_write_b16_d16_hi v100, v24 offset:720
	ds_write_b16 v100, v25 offset:864
	ds_write_b16_d16_hi v100, v25 offset:1008
	s_waitcnt vmcnt(4)
	ds_write_b16 v100, v18 offset:9216
	ds_write_b16_d16_hi v100, v18 offset:9360
	ds_write_b16 v100, v19 offset:9504
	ds_write_b16_d16_hi v100, v19 offset:9648
	ds_write_b16 v100, v20 offset:9792
	ds_write_b16_d16_hi v100, v20 offset:9936
	ds_write_b16 v100, v21 offset:10080
	ds_write_b16_d16_hi v100, v21 offset:10224
	s_waitcnt vmcnt(3)
	ds_write_b16 v100, v12 offset:18432
	ds_write_b16_d16_hi v100, v12 offset:18576
	ds_write_b16 v100, v13 offset:18720
	ds_write_b16_d16_hi v100, v13 offset:18864
	ds_write_b16 v100, v14 offset:19008
	ds_write_b16_d16_hi v100, v14 offset:19152
	ds_write_b16 v100, v15 offset:19296
	ds_write_b16_d16_hi v100, v15 offset:19440
	s_waitcnt vmcnt(2)
	ds_write_b16 v100, v4 offset:27648
	ds_write_b16_d16_hi v100, v4 offset:27792
	ds_write_b16 v100, v5 offset:27936
	ds_write_b16_d16_hi v100, v5 offset:28080
	ds_write_b16 v100, v6 offset:28224
	ds_write_b16_d16_hi v100, v6 offset:28368
	ds_write_b16 v100, v7 offset:28512
	ds_write_b16_d16_hi v100, v7 offset:28656
	s_waitcnt vmcnt(1)
	ds_write_b16 v100, v8 offset:36864
	ds_write_b16_d16_hi v100, v8 offset:37008
	ds_write_b16 v100, v9 offset:37152
	ds_write_b16_d16_hi v100, v9 offset:37296
	ds_write_b16 v100, v10 offset:37440
	ds_write_b16_d16_hi v100, v10 offset:37584
	ds_write_b16 v100, v11 offset:37728
	ds_write_b16_d16_hi v100, v11 offset:37872
	s_waitcnt vmcnt(0)
	ds_write_b16 v100, v0 offset:46080
	ds_write_b16_d16_hi v100, v0 offset:46224
	ds_write_b16 v100, v1 offset:46368
	ds_write_b16_d16_hi v100, v1 offset:46512
	ds_write_b16 v100, v2 offset:46656
	ds_write_b16_d16_hi v100, v2 offset:46800
	ds_write_b16 v100, v3 offset:46944
	ds_write_b16_d16_hi v100, v3 offset:47088
	s_waitcnt lgkmcnt(0)
	s_barrier
; __device__ __forceinline__ unsigned pk2(float lo, float hi) { return pg8::cvt_pk_bf16(lo, hi); }
; __device__ __forceinline__ f32x4 mma16(bf16x8 a, bf16x8 b, f32x4 c) { return __builtin_amdgcn_mfma_f32_16x16x32_bf16(a, b, c, 0, 0, 0); }
; __device__ __forceinline__ void ma_ret_item(const Params& p, ldsp lds, int item) {
;     ...
; #pragma unroll
;         for (int ks = 0; ks < 2; ++ks) { const bf16x8 bf = ldfrag(VTt, (16 * wave + l15) * 72 + 32 * ks + 8 * q4);
; #pragma unroll
;             for (int i = 0; i < 16; ++i) acc[i] = mma16(ldfrag(KTt, (16 * i + l15) * 72 + 32 * ks + 8 * q4), bf, acc[i]); }
;         __syncthreads(); }
;     bf16_t* HL = (bf16_t*)(p.ws + WS_HL) + (((size_t)bh * 8 + sc) * 512 + es * 128 + 16 * wave + l15) * 256;
; #pragma unroll
;     for (int i = 0; i < 16; ++i) { u32x2 w; w.x = pk2(acc[i][0], acc[i][1]); w.y = pk2(acc[i][2], acc[i][3]); *(u32x2*)(HL + 16 * i + 4 * q4) = w; }
	ds_read_b128 v[0:3], v132
	ds_read_b128 v[4:7], v130 offset:36864
	ds_read_b128 v[8:11], v131
	ds_read_b128 v[12:15], v130 offset:36928
	ds_read_b128 v[18:21], v129
	ds_read_b128 v[22:25], v128
	s_waitcnt lgkmcnt(4)
	v_mfma_f32_16x16x32_bf16 v[0:3], v[0:3], v[4:7], v[26:29]
	s_ashr_i32 s1, s0, 31
	v_readlane_b32 s10, v255, 9
	s_lshl_b64 s[0:1], s[0:1], 12
	s_waitcnt lgkmcnt(3)
	v_mfma_f32_16x16x32_bf16 v[8:11], v[8:11], v[4:7], v[34:37]
	ds_read_b128 v[26:29], v127
	v_readlane_b32 s11, v255, 10
	s_or_b64 s[0:1], s[0:1], s[10:11]
	s_waitcnt lgkmcnt(2)
	v_mfma_f32_16x16x32_bf16 v[18:21], v[18:21], v[4:7], v[38:41]
	ds_read_b128 v[34:37], v126
	s_ashr_i32 s9, s8, 31
	s_add_i32 s12, s12, 1
	s_waitcnt lgkmcnt(2)
	v_mfma_f32_16x16x32_bf16 v[22:25], v[22:25], v[4:7], v[42:45]
	ds_read_b128 v[38:41], v125
	s_cmp_eq_u32 s12, 4
	s_nop 0
	ds_read_b128 v[42:45], v124
	s_waitcnt lgkmcnt(3)
	v_mfma_f32_16x16x32_bf16 v[26:29], v[26:29], v[4:7], v[46:49]
	s_waitcnt lgkmcnt(2)
	v_mfma_f32_16x16x32_bf16 v[34:37], v[34:37], v[4:7], v[50:53]
	s_nop 0
	ds_read_b128 v[46:49], v123
	s_nop 0
	ds_read_b128 v[50:53], v122
	s_waitcnt lgkmcnt(3)
	v_mfma_f32_16x16x32_bf16 v[38:41], v[38:41], v[4:7], v[54:57]
	s_waitcnt lgkmcnt(2)
	v_mfma_f32_16x16x32_bf16 v[42:45], v[42:45], v[4:7], v[58:61]
	s_nop 0
	ds_read_b128 v[54:57], v121
	s_nop 0
	ds_read_b128 v[58:61], v120
	s_waitcnt lgkmcnt(3)
	v_mfma_f32_16x16x32_bf16 v[46:49], v[46:49], v[4:7], v[62:65]
	s_waitcnt lgkmcnt(2)
	v_mfma_f32_16x16x32_bf16 v[50:53], v[50:53], v[4:7], v[66:69]
	s_nop 0
	ds_read_b128 v[62:65], v119
	s_nop 0
	ds_read_b128 v[66:69], v118
	s_waitcnt lgkmcnt(3)
	v_mfma_f32_16x16x32_bf16 v[54:57], v[54:57], v[4:7], v[70:73]
	s_waitcnt lgkmcnt(2)
	v_mfma_f32_16x16x32_bf16 v[58:61], v[58:61], v[4:7], v[74:77]
	s_nop 0
	ds_read_b128 v[70:73], v117
	s_nop 0
	ds_read_b128 v[74:77], v116
	s_waitcnt lgkmcnt(3)
	v_mfma_f32_16x16x32_bf16 v[62:65], v[62:65], v[4:7], v[78:81]
	s_waitcnt lgkmcnt(2)
	v_mfma_f32_16x16x32_bf16 v[66:69], v[66:69], v[4:7], v[82:85]
	s_nop 0
	ds_read_b128 v[78:81], v115
	s_waitcnt lgkmcnt(2)
	v_mfma_f32_16x16x32_bf16 v[70:73], v[70:73], v[4:7], v[86:89]
	s_waitcnt lgkmcnt(1)
	v_mfma_f32_16x16x32_bf16 v[4:7], v[74:77], v[4:7], v[30:33]
	ds_read_b128 v[74:77], v113
	s_nop 1
	ds_read_b128 v[30:33], v114
	s_waitcnt lgkmcnt(0)
	v_mfma_f32_16x16x32_bf16 v[8:11], v[30:33], v[12:15], v[8:11]
	ds_read_b128 v[30:33], v112
	v_mfma_f32_16x16x32_bf16 v[18:21], v[74:77], v[12:15], v[18:21]
	ds_read_b128 v[74:77], v111
	s_waitcnt lgkmcnt(1)
	v_mfma_f32_16x16x32_bf16 v[22:25], v[30:33], v[12:15], v[22:25]
	ds_read_b128 v[30:33], v110
	s_waitcnt lgkmcnt(1)
	v_mfma_f32_16x16x32_bf16 v[26:29], v[74:77], v[12:15], v[26:29]
	ds_read_b128 v[74:77], v109
	s_waitcnt lgkmcnt(1)
	v_mfma_f32_16x16x32_bf16 v[30:33], v[30:33], v[12:15], v[34:37]
	s_nop 2
	ds_read_b128 v[34:37], v108
	s_waitcnt lgkmcnt(1)
	v_mfma_f32_16x16x32_bf16 v[38:41], v[74:77], v[12:15], v[38:41]
	ds_read_b128 v[74:77], v107
	s_waitcnt lgkmcnt(1)
	v_mfma_f32_16x16x32_bf16 v[34:37], v[34:37], v[12:15], v[42:45]
	s_nop 2
	ds_read_b128 v[42:45], v106
	s_waitcnt lgkmcnt(1)
	v_mfma_f32_16x16x32_bf16 v[46:49], v[74:77], v[12:15], v[46:49]
	ds_read_b128 v[74:77], v105
	s_waitcnt lgkmcnt(1)
	v_mfma_f32_16x16x32_bf16 v[42:45], v[42:45], v[12:15], v[50:53]
	s_nop 2
	ds_read_b128 v[50:53], v104
	v_mfma_f32_16x16x32_bf16 v[0:3], v[78:81], v[12:15], v[0:3]
	s_waitcnt lgkmcnt(1)
	v_mfma_f32_16x16x32_bf16 v[54:57], v[74:77], v[12:15], v[54:57]
	ds_read_b128 v[74:77], v103
	ds_read_b128 v[78:81], v102
	s_waitcnt lgkmcnt(2)
	v_mfma_f32_16x16x32_bf16 v[50:53], v[50:53], v[12:15], v[58:61]
	s_nop 2
	ds_read_b128 v[58:61], v101
	ds_read_b128 v[82:85], v16
	s_waitcnt lgkmcnt(0)
	s_barrier
	v_mfma_f32_16x16x32_bf16 v[58:61], v[58:61], v[12:15], v[70:73]
	v_cvt_pk_bf16_f32 v0, v0, v1
	v_cvt_pk_bf16_f32 v1, v2, v3
	v_mfma_f32_16x16x32_bf16 v[62:65], v[74:77], v[12:15], v[62:65]
	s_nop 1
	v_or_b32_e32 v70, s0, v95
	v_mov_b32_e32 v71, s1
	v_lshl_add_u64 v[70:71], v[70:71], 0, s[8:9]
	v_readlane_b32 s0, v253, 34
	v_mfma_f32_16x16x32_bf16 v[66:69], v[78:81], v[12:15], v[66:69]
	v_readlane_b32 s1, v253, 35
	v_mov_b32_e32 v95, v17
	v_mfma_f32_16x16x32_bf16 v[4:7], v[82:85], v[12:15], v[4:7]
	v_lshlrev_b64 v[12:13], 9, v[70:71]
	v_lshl_add_u64 v[12:13], s[0:1], 0, v[12:13]
	v_lshl_add_u64 v[12:13], v[12:13], 0, v[94:95]
	global_store_dwordx2 v[12:13], v[0:1], off
	v_cvt_pk_bf16_f32 v0, v8, v9
	v_cvt_pk_bf16_f32 v1, v10, v11
	global_store_dwordx2 v[12:13], v[0:1], off offset:32
	v_cvt_pk_bf16_f32 v0, v18, v19
	v_cvt_pk_bf16_f32 v1, v20, v21
	global_store_dwordx2 v[12:13], v[0:1], off offset:64
	v_cvt_pk_bf16_f32 v0, v22, v23
	v_cvt_pk_bf16_f32 v1, v24, v25
	global_store_dwordx2 v[12:13], v[0:1], off offset:96
	v_cvt_pk_bf16_f32 v0, v26, v27
	v_cvt_pk_bf16_f32 v1, v28, v29
	global_store_dwordx2 v[12:13], v[0:1], off offset:128
	v_cvt_pk_bf16_f32 v0, v30, v31
	v_cvt_pk_bf16_f32 v1, v32, v33
	global_store_dwordx2 v[12:13], v[0:1], off offset:160
	v_cvt_pk_bf16_f32 v0, v38, v39
	v_cvt_pk_bf16_f32 v1, v40, v41
	global_store_dwordx2 v[12:13], v[0:1], off offset:192
	v_cvt_pk_bf16_f32 v0, v34, v35
	v_cvt_pk_bf16_f32 v1, v36, v37
	global_store_dwordx2 v[12:13], v[0:1], off offset:224
	v_cvt_pk_bf16_f32 v0, v46, v47
	v_cvt_pk_bf16_f32 v1, v48, v49
	global_store_dwordx2 v[12:13], v[0:1], off offset:256
	v_cvt_pk_bf16_f32 v0, v42, v43
	v_cvt_pk_bf16_f32 v1, v44, v45
	global_store_dwordx2 v[12:13], v[0:1], off offset:288
	v_cvt_pk_bf16_f32 v0, v54, v55
	v_cvt_pk_bf16_f32 v1, v56, v57
	global_store_dwordx2 v[12:13], v[0:1], off offset:320
	v_cvt_pk_bf16_f32 v0, v50, v51
	v_cvt_pk_bf16_f32 v1, v52, v53
	global_store_dwordx2 v[12:13], v[0:1], off offset:352
	v_cvt_pk_bf16_f32 v0, v62, v63
	v_cvt_pk_bf16_f32 v1, v64, v65
	global_store_dwordx2 v[12:13], v[0:1], off offset:384
	v_cvt_pk_bf16_f32 v0, v66, v67
	v_cvt_pk_bf16_f32 v1, v68, v69
	global_store_dwordx2 v[12:13], v[0:1], off offset:416
	v_cvt_pk_bf16_f32 v0, v58, v59
	v_cvt_pk_bf16_f32 v1, v60, v61
	global_store_dwordx2 v[12:13], v[0:1], off offset:448
	v_cvt_pk_bf16_f32 v0, v4, v5
	v_cvt_pk_bf16_f32 v1, v6, v7
	global_store_dwordx2 v[12:13], v[0:1], off offset:480
	s_cbranch_scc0 .LBB0_677
